# long-conv single-column MFMA groups: B read first, resident-A MFMA first
# speedup vs baseline: 1.0020x; 1.0008x over previous
; #define MFMA(a, b, c) __builtin_amdgcn_mfma_f32_32x32x16_bf16((a), (b), (c), 0, 0, 0)
; __device__ __forceinline__ void toeplitz_item(const Params& p, int layer, int half, int c, bf16* sm, int dry, unsigned* done_ctr) {
;     ...
;     for (int Dl = 0; Dl < 4; ++Dl) {
;       const int D = D0 + Dl;
;       bool actv[2];
;       int bblk[2];
; #pragma unroll
;       for (int ni = 0; ni < 2; ++ni) {
;         const int nlo = 32 * wn + 64 * ni;
;         actv[ni] = half ? true : !((nlo + 31 - D < 0) || (nlo - D >= 128));
;         const int n = nlo + r;
;         const int src = n - D;
;         const bool valid = half ? ((unsigned)((n & 15) - D) < 16u) : ((unsigned)src < 128u);
;         bblk[ni] = valid ? src : 128;
;       }
;       if (!actv[0] && !actv[1]) continue;
;       const int tb = 16 * (3 - Dl) + 16 + hh - rt;
;       const bf16* ap0 = sW + (aq * 83 + tb - 4 * (2 * wm)) * 8;
;       const bf16* bp0 = sU + bblk[0] * 136 + 8 * hh;
;       const bf16* bp1 = sU + bblk[1] * 136 + 8 * hh;
;       if (actv[0] && actv[1]) {
; #pragma unroll
;         for (int ks = 0; ks < 8; ++ks) {
;           const s8v a0 = *(const s8v*)(ap0 + 16 * ks), a1 = *(const s8v*)(ap0 - 32 + 16 * ks);
;           const s8v b0 = *(const s8v*)(bp0 + 16 * ks), b1 = *(const s8v*)(bp1 + 16 * ks);
;           acc[0][0] = MFMA(a0, b0, acc[0][0]);
;           acc[1][0] = MFMA(a1, b0, acc[1][0]);
;           acc[0][1] = MFMA(a0, b1, acc[0][1]);
;           acc[1][1] = MFMA(a1, b1, acc[1][1]);
;         }
.LBB0_1147:
	s_or_b64 exec, exec, s[2:3]
	v_add_u32_e32 v66, 3, v123
	v_add_u32_e32 v124, s74, v122
	v_cmp_gt_u32_e64 s[2:3], 16, v66
	v_add_u32_e32 v66, 0x1100, v124
	ds_read_b128 v[70:73], v89 offset:35088
	v_cndmask_b32_e64 v66, v228, v66, s[2:3]
	v_add_u32_e32 v125, v90, v66
	ds_read_b128 v[66:69], v89 offset:35024
	ds_read_b128 v[74:77], v125
	v_add_u32_e32 v78, 0x5500, v124
	s_waitcnt lgkmcnt(0)
	v_mfma_f32_32x32x16_bf16 v[50:65], v[70:73], v[74:77], v[50:65]
	s_addk_i32 s74, 0xfbc0
	s_cmpk_eq_i32 s74, 0xe240
	v_mfma_f32_32x32x16_bf16 v[18:33], v[66:69], v[74:77], v[18:33]
	v_cndmask_b32_e64 v74, v228, v78, s[2:3]
	v_add_u32_e32 v134, v90, v74
	ds_read_b128 v[74:77], v134
	ds_read_b128 v[78:81], v89 offset:35120
	ds_read_b128 v[126:129], v125 offset:32
	s_waitcnt lgkmcnt(2)
	v_mfma_f32_32x32x16_bf16 v[34:49], v[70:73], v[74:77], v[34:49]
	v_mfma_f32_32x32x16_bf16 v[2:17], v[66:69], v[74:77], v[2:17]
	ds_read_b128 v[74:77], v89 offset:35056
	s_waitcnt lgkmcnt(1)
	v_mfma_f32_32x32x16_bf16 v[50:65], v[78:81], v[126:129], v[50:65]
	s_waitcnt lgkmcnt(0)
	v_mfma_f32_32x32x16_bf16 v[18:33], v[74:77], v[126:129], v[18:33]
	ds_read_b128 v[126:129], v134 offset:32
	s_waitcnt lgkmcnt(0)
	v_mfma_f32_32x32x16_bf16 v[34:49], v[78:81], v[126:129], v[34:49]
	v_mfma_f32_32x32x16_bf16 v[2:17], v[74:77], v[126:129], v[2:17]
	ds_read_b128 v[130:133], v125 offset:64
	ds_read_b128 v[200:203], v134 offset:64
	ds_read_b128 v[126:129], v89 offset:35152
	s_waitcnt lgkmcnt(2)
	v_mfma_f32_32x32x16_bf16 v[18:33], v[70:73], v[130:133], v[18:33]
	s_waitcnt lgkmcnt(1)
	v_mfma_f32_32x32x16_bf16 v[2:17], v[70:73], v[200:203], v[2:17]
	s_waitcnt lgkmcnt(0)
	v_mfma_f32_32x32x16_bf16 v[50:65], v[126:129], v[130:133], v[50:65]
	v_mfma_f32_32x32x16_bf16 v[34:49], v[126:129], v[200:203], v[34:49]
	ds_read_b128 v[130:133], v125 offset:96
	ds_read_b128 v[200:203], v134 offset:96
	ds_read_b128 v[70:73], v89 offset:35184
	s_waitcnt lgkmcnt(2)
	v_mfma_f32_32x32x16_bf16 v[18:33], v[78:81], v[130:133], v[18:33]
	s_waitcnt lgkmcnt(1)
	v_mfma_f32_32x32x16_bf16 v[2:17], v[78:81], v[200:203], v[2:17]
	s_waitcnt lgkmcnt(0)
	v_mfma_f32_32x32x16_bf16 v[50:65], v[70:73], v[130:133], v[50:65]
	v_mfma_f32_32x32x16_bf16 v[34:49], v[70:73], v[200:203], v[34:49]
	ds_read_b128 v[130:133], v125 offset:128
	ds_read_b128 v[200:203], v134 offset:128
	ds_read_b128 v[78:81], v89 offset:35216
	s_waitcnt lgkmcnt(2)
	v_mfma_f32_32x32x16_bf16 v[18:33], v[126:129], v[130:133], v[18:33]
	s_waitcnt lgkmcnt(1)
	v_mfma_f32_32x32x16_bf16 v[2:17], v[126:129], v[200:203], v[2:17]
	s_waitcnt lgkmcnt(0)
	v_mfma_f32_32x32x16_bf16 v[50:65], v[78:81], v[130:133], v[50:65]
	v_mfma_f32_32x32x16_bf16 v[34:49], v[78:81], v[200:203], v[34:49]
	ds_read_b128 v[130:133], v125 offset:160
	ds_read_b128 v[200:203], v134 offset:160
	ds_read_b128 v[126:129], v89 offset:35248
	s_waitcnt lgkmcnt(2)
	v_mfma_f32_32x32x16_bf16 v[18:33], v[70:73], v[130:133], v[18:33]
	s_waitcnt lgkmcnt(1)
	v_mfma_f32_32x32x16_bf16 v[2:17], v[70:73], v[200:203], v[2:17]
	s_waitcnt lgkmcnt(0)
	v_mfma_f32_32x32x16_bf16 v[50:65], v[126:129], v[130:133], v[50:65]
	v_mfma_f32_32x32x16_bf16 v[34:49], v[126:129], v[200:203], v[34:49]
	ds_read_b128 v[130:133], v125 offset:192
	ds_read_b128 v[200:203], v134 offset:192
	ds_read_b128 v[70:73], v89 offset:35280
	s_waitcnt lgkmcnt(2)
	v_mfma_f32_32x32x16_bf16 v[18:33], v[78:81], v[130:133], v[18:33]
	s_waitcnt lgkmcnt(1)
	v_mfma_f32_32x32x16_bf16 v[2:17], v[78:81], v[200:203], v[2:17]
	s_waitcnt lgkmcnt(0)
	v_mfma_f32_32x32x16_bf16 v[50:65], v[70:73], v[130:133], v[50:65]
	v_mfma_f32_32x32x16_bf16 v[34:49], v[70:73], v[200:203], v[34:49]
	ds_read_b128 v[70:73], v89 offset:35312
	ds_read_b128 v[78:81], v125 offset:224
	v_add_u32_e32 v130, 0x53f0, v124
	s_waitcnt lgkmcnt(0)
	v_mfma_f32_32x32x16_bf16 v[50:65], v[70:73], v[78:81], v[50:65]
	v_mfma_f32_32x32x16_bf16 v[18:33], v[126:129], v[78:81], v[18:33]
	ds_read_b128 v[78:81], v134 offset:224
	s_waitcnt lgkmcnt(0)
	v_mfma_f32_32x32x16_bf16 v[34:49], v[70:73], v[78:81], v[34:49]
	v_add_u32_e32 v70, 2, v123
	v_cmp_gt_u32_e64 s[2:3], 16, v70
	v_add_u32_e32 v70, 0xff0, v124
	s_nop 0
	v_cndmask_b32_e64 v70, v228, v70, s[2:3]
	v_add_u32_e32 v125, v90, v70
	ds_read_b128 v[70:73], v89 offset:34768
	v_mfma_f32_32x32x16_bf16 v[2:17], v[126:129], v[78:81], v[2:17]
	ds_read_b128 v[78:81], v125
	ds_read_b128 v[126:129], v89 offset:34832
	s_waitcnt lgkmcnt(1)
	v_mfma_f32_32x32x16_bf16 v[18:33], v[70:73], v[78:81], v[18:33]
	s_waitcnt lgkmcnt(0)
	v_mfma_f32_32x32x16_bf16 v[50:65], v[126:129], v[78:81], v[50:65]
	v_cndmask_b32_e64 v78, v228, v130, s[2:3]
	v_add_u32_e32 v142, v90, v78
	ds_read_b128 v[78:81], v142
	ds_read_b128 v[130:133], v89 offset:34864
	ds_read_b128 v[134:137], v125 offset:32
	s_waitcnt lgkmcnt(2)
	v_mfma_f32_32x32x16_bf16 v[34:49], v[126:129], v[78:81], v[34:49]
	v_mfma_f32_32x32x16_bf16 v[2:17], v[70:73], v[78:81], v[2:17]
	ds_read_b128 v[78:81], v89 offset:34800
	s_waitcnt lgkmcnt(1)
	v_mfma_f32_32x32x16_bf16 v[50:65], v[130:133], v[134:137], v[50:65]
	s_waitcnt lgkmcnt(0)
	v_mfma_f32_32x32x16_bf16 v[18:33], v[78:81], v[134:137], v[18:33]
	ds_read_b128 v[134:137], v142 offset:32
	s_waitcnt lgkmcnt(0)
	v_mfma_f32_32x32x16_bf16 v[34:49], v[130:133], v[134:137], v[34:49]
	v_mfma_f32_32x32x16_bf16 v[2:17], v[78:81], v[134:137], v[2:17]
	ds_read_b128 v[138:141], v125 offset:64
	ds_read_b128 v[200:203], v142 offset:64
	ds_read_b128 v[134:137], v89 offset:34896
	s_waitcnt lgkmcnt(2)
	v_mfma_f32_32x32x16_bf16 v[18:33], v[126:129], v[138:141], v[18:33]
	s_waitcnt lgkmcnt(1)
	v_mfma_f32_32x32x16_bf16 v[2:17], v[126:129], v[200:203], v[2:17]
	s_waitcnt lgkmcnt(0)
; #define MFMA(a, b, c) __builtin_amdgcn_mfma_f32_32x32x16_bf16((a), (b), (c), 0, 0, 0)
; __device__ __forceinline__ void toeplitz_item(const Params& p, int layer, int half, int c, bf16* sm, int dry, unsigned* done_ctr) {
;     ...
;     for (int Dl = 0; Dl < 4; ++Dl) {
;       const int D = D0 + Dl;
;       bool actv[2];
;       int bblk[2];
; #pragma unroll
;       for (int ni = 0; ni < 2; ++ni) {
;         const int nlo = 32 * wn + 64 * ni;
;         actv[ni] = half ? true : !((nlo + 31 - D < 0) || (nlo - D >= 128));
;         const int n = nlo + r;
;         const int src = n - D;
;         const bool valid = half ? ((unsigned)((n & 15) - D) < 16u) : ((unsigned)src < 128u);
;         bblk[ni] = valid ? src : 128;
;       }
;       if (!actv[0] && !actv[1]) continue;
;       const int tb = 16 * (3 - Dl) + 16 + hh - rt;
;       const bf16* ap0 = sW + (aq * 83 + tb - 4 * (2 * wm)) * 8;
;       const bf16* bp0 = sU + bblk[0] * 136 + 8 * hh;
;       const bf16* bp1 = sU + bblk[1] * 136 + 8 * hh;
;       if (actv[0] && actv[1]) {
; #pragma unroll
;         for (int ks = 0; ks < 8; ++ks) {
;           const s8v a0 = *(const s8v*)(ap0 + 16 * ks), a1 = *(const s8v*)(ap0 - 32 + 16 * ks);
;           const s8v b0 = *(const s8v*)(bp0 + 16 * ks), b1 = *(const s8v*)(bp1 + 16 * ks);
;           acc[0][0] = MFMA(a0, b0, acc[0][0]);
;           acc[1][0] = MFMA(a1, b0, acc[1][0]);
;           acc[0][1] = MFMA(a0, b1, acc[0][1]);
;           acc[1][1] = MFMA(a1, b1, acc[1][1]);
;         }
	v_mfma_f32_32x32x16_bf16 v[50:65], v[134:137], v[138:141], v[50:65]
	v_mfma_f32_32x32x16_bf16 v[34:49], v[134:137], v[200:203], v[34:49]
	ds_read_b128 v[138:141], v125 offset:96
	ds_read_b128 v[200:203], v142 offset:96
	ds_read_b128 v[126:129], v89 offset:34928
	s_waitcnt lgkmcnt(2)
	v_mfma_f32_32x32x16_bf16 v[18:33], v[130:133], v[138:141], v[18:33]
	s_waitcnt lgkmcnt(1)
	v_mfma_f32_32x32x16_bf16 v[2:17], v[130:133], v[200:203], v[2:17]
	s_waitcnt lgkmcnt(0)
	v_mfma_f32_32x32x16_bf16 v[50:65], v[126:129], v[138:141], v[50:65]
	v_mfma_f32_32x32x16_bf16 v[34:49], v[126:129], v[200:203], v[34:49]
	ds_read_b128 v[138:141], v125 offset:128
	ds_read_b128 v[200:203], v142 offset:128
	ds_read_b128 v[130:133], v89 offset:34960
	s_waitcnt lgkmcnt(2)
	v_mfma_f32_32x32x16_bf16 v[18:33], v[134:137], v[138:141], v[18:33]
	s_waitcnt lgkmcnt(1)
	v_mfma_f32_32x32x16_bf16 v[2:17], v[134:137], v[200:203], v[2:17]
	s_waitcnt lgkmcnt(0)
	v_mfma_f32_32x32x16_bf16 v[50:65], v[130:133], v[138:141], v[50:65]
	v_mfma_f32_32x32x16_bf16 v[34:49], v[130:133], v[200:203], v[34:49]
	ds_read_b128 v[138:141], v125 offset:160
	ds_read_b128 v[134:137], v89 offset:34992
	s_waitcnt lgkmcnt(1)
	v_mfma_f32_32x32x16_bf16 v[18:33], v[126:129], v[138:141], v[18:33]
	s_waitcnt lgkmcnt(0)
	v_mfma_f32_32x32x16_bf16 v[50:65], v[134:137], v[138:141], v[50:65]
	ds_read_b128 v[138:141], v142 offset:160
	s_waitcnt lgkmcnt(0)
	v_mfma_f32_32x32x16_bf16 v[2:17], v[126:129], v[138:141], v[2:17]
	ds_read_b128 v[126:129], v125 offset:192
	v_mfma_f32_32x32x16_bf16 v[34:49], v[134:137], v[138:141], v[34:49]
	s_waitcnt lgkmcnt(0)
	v_mfma_f32_32x32x16_bf16 v[50:65], v[66:69], v[126:129], v[50:65]
	v_mfma_f32_32x32x16_bf16 v[18:33], v[130:133], v[126:129], v[18:33]
	ds_read_b128 v[126:129], v142 offset:192
	s_waitcnt lgkmcnt(0)
	v_mfma_f32_32x32x16_bf16 v[34:49], v[66:69], v[126:129], v[34:49]
	ds_read_b128 v[66:69], v125 offset:224
	v_mfma_f32_32x32x16_bf16 v[2:17], v[130:133], v[126:129], v[2:17]
	ds_read_b128 v[126:129], v89 offset:34576
	v_add_u32_e32 v130, 0x52e0, v124
	s_waitcnt lgkmcnt(1)
	v_mfma_f32_32x32x16_bf16 v[50:65], v[74:77], v[66:69], v[50:65]
	v_mfma_f32_32x32x16_bf16 v[18:33], v[134:137], v[66:69], v[18:33]
	ds_read_b128 v[66:69], v142 offset:224
	s_waitcnt lgkmcnt(0)
	v_mfma_f32_32x32x16_bf16 v[34:49], v[74:77], v[66:69], v[34:49]
	v_mfma_f32_32x32x16_bf16 v[2:17], v[134:137], v[66:69], v[2:17]
	v_add_u32_e32 v66, 1, v123
	v_cmp_gt_u32_e64 s[2:3], 16, v66
	v_add_u32_e32 v66, 0xee0, v124
	s_nop 0
	v_cndmask_b32_e64 v66, v228, v66, s[2:3]
	v_add_u32_e32 v125, v90, v66
	ds_read_b128 v[66:69], v89 offset:34512
	ds_read_b128 v[74:77], v125
	s_waitcnt lgkmcnt(0)
	v_mfma_f32_32x32x16_bf16 v[50:65], v[126:129], v[74:77], v[50:65]
	v_mfma_f32_32x32x16_bf16 v[18:33], v[66:69], v[74:77], v[18:33]
	v_cndmask_b32_e64 v74, v228, v130, s[2:3]
	v_add_u32_e32 v142, v90, v74
	ds_read_b128 v[74:77], v142
	ds_read_b128 v[130:133], v89 offset:34608
	ds_read_b128 v[134:137], v125 offset:32
	v_cmp_gt_u32_e64 s[2:3], 16, v123
	v_add_u32_e32 v123, -4, v123
	s_waitcnt lgkmcnt(2)
	v_mfma_f32_32x32x16_bf16 v[34:49], v[126:129], v[74:77], v[34:49]
	v_mfma_f32_32x32x16_bf16 v[2:17], v[66:69], v[74:77], v[2:17]
	ds_read_b128 v[74:77], v89 offset:34544
	s_waitcnt lgkmcnt(1)
	v_mfma_f32_32x32x16_bf16 v[50:65], v[130:133], v[134:137], v[50:65]
	s_waitcnt lgkmcnt(0)
	v_mfma_f32_32x32x16_bf16 v[18:33], v[74:77], v[134:137], v[18:33]
	ds_read_b128 v[134:137], v142 offset:32
	s_waitcnt lgkmcnt(0)
	v_mfma_f32_32x32x16_bf16 v[34:49], v[130:133], v[134:137], v[34:49]
	v_mfma_f32_32x32x16_bf16 v[2:17], v[74:77], v[134:137], v[2:17]
	ds_read_b128 v[138:141], v125 offset:64
	ds_read_b128 v[200:203], v142 offset:64
	ds_read_b128 v[134:137], v89 offset:34640
	s_waitcnt lgkmcnt(2)
	v_mfma_f32_32x32x16_bf16 v[18:33], v[126:129], v[138:141], v[18:33]
	s_waitcnt lgkmcnt(1)
	v_mfma_f32_32x32x16_bf16 v[2:17], v[126:129], v[200:203], v[2:17]
	s_waitcnt lgkmcnt(0)
	v_mfma_f32_32x32x16_bf16 v[50:65], v[134:137], v[138:141], v[50:65]
	v_mfma_f32_32x32x16_bf16 v[34:49], v[134:137], v[200:203], v[34:49]
	ds_read_b128 v[138:141], v125 offset:96
	ds_read_b128 v[200:203], v142 offset:96
	ds_read_b128 v[126:129], v89 offset:34672
	s_waitcnt lgkmcnt(2)
	v_mfma_f32_32x32x16_bf16 v[18:33], v[130:133], v[138:141], v[18:33]
	s_waitcnt lgkmcnt(1)
	v_mfma_f32_32x32x16_bf16 v[2:17], v[130:133], v[200:203], v[2:17]
	s_waitcnt lgkmcnt(0)
	v_mfma_f32_32x32x16_bf16 v[50:65], v[126:129], v[138:141], v[50:65]
	v_mfma_f32_32x32x16_bf16 v[34:49], v[126:129], v[200:203], v[34:49]
	ds_read_b128 v[138:141], v125 offset:128
	ds_read_b128 v[200:203], v142 offset:128
	ds_read_b128 v[130:133], v89 offset:34704
	s_waitcnt lgkmcnt(2)
	v_mfma_f32_32x32x16_bf16 v[18:33], v[134:137], v[138:141], v[18:33]
	s_waitcnt lgkmcnt(1)
	v_mfma_f32_32x32x16_bf16 v[2:17], v[134:137], v[200:203], v[2:17]
	s_waitcnt lgkmcnt(0)
	v_mfma_f32_32x32x16_bf16 v[50:65], v[130:133], v[138:141], v[50:65]
	v_mfma_f32_32x32x16_bf16 v[34:49], v[130:133], v[200:203], v[34:49]
	ds_read_b128 v[138:141], v125 offset:160
	ds_read_b128 v[134:137], v89 offset:34736
	s_waitcnt lgkmcnt(1)
; #define MFMA(a, b, c) __builtin_amdgcn_mfma_f32_32x32x16_bf16((a), (b), (c), 0, 0, 0)
; __device__ __forceinline__ void toeplitz_item(const Params& p, int layer, int half, int c, bf16* sm, int dry, unsigned* done_ctr) {
;     ...
;     for (int Dl = 0; Dl < 4; ++Dl) {
;       const int D = D0 + Dl;
;       bool actv[2];
;       int bblk[2];
; #pragma unroll
;       for (int ni = 0; ni < 2; ++ni) {
;         const int nlo = 32 * wn + 64 * ni;
;         actv[ni] = half ? true : !((nlo + 31 - D < 0) || (nlo - D >= 128));
;         const int n = nlo + r;
;         const int src = n - D;
;         const bool valid = half ? ((unsigned)((n & 15) - D) < 16u) : ((unsigned)src < 128u);
;         bblk[ni] = valid ? src : 128;
;       }
;       if (!actv[0] && !actv[1]) continue;
;       const int tb = 16 * (3 - Dl) + 16 + hh - rt;
;       const bf16* ap0 = sW + (aq * 83 + tb - 4 * (2 * wm)) * 8;
;       const bf16* bp0 = sU + bblk[0] * 136 + 8 * hh;
;       const bf16* bp1 = sU + bblk[1] * 136 + 8 * hh;
;       if (actv[0] && actv[1]) {
; #pragma unroll
;         for (int ks = 0; ks < 8; ++ks) {
;           const s8v a0 = *(const s8v*)(ap0 + 16 * ks), a1 = *(const s8v*)(ap0 - 32 + 16 * ks);
;           const s8v b0 = *(const s8v*)(bp0 + 16 * ks), b1 = *(const s8v*)(bp1 + 16 * ks);
;           acc[0][0] = MFMA(a0, b0, acc[0][0]);
;           acc[1][0] = MFMA(a1, b0, acc[1][0]);
;           acc[0][1] = MFMA(a0, b1, acc[0][1]);
;           acc[1][1] = MFMA(a1, b1, acc[1][1]);
;         }
	v_mfma_f32_32x32x16_bf16 v[18:33], v[126:129], v[138:141], v[18:33]
	s_waitcnt lgkmcnt(0)
	v_mfma_f32_32x32x16_bf16 v[50:65], v[134:137], v[138:141], v[50:65]
	ds_read_b128 v[138:141], v142 offset:160
	s_waitcnt lgkmcnt(0)
	v_mfma_f32_32x32x16_bf16 v[2:17], v[126:129], v[138:141], v[2:17]
	ds_read_b128 v[126:129], v125 offset:192
	v_mfma_f32_32x32x16_bf16 v[34:49], v[134:137], v[138:141], v[34:49]
	s_waitcnt lgkmcnt(0)
	v_mfma_f32_32x32x16_bf16 v[50:65], v[70:73], v[126:129], v[50:65]
	v_mfma_f32_32x32x16_bf16 v[18:33], v[130:133], v[126:129], v[18:33]
	ds_read_b128 v[126:129], v142 offset:192
	s_waitcnt lgkmcnt(0)
	v_mfma_f32_32x32x16_bf16 v[34:49], v[70:73], v[126:129], v[34:49]
	ds_read_b128 v[70:73], v125 offset:224
	v_mfma_f32_32x32x16_bf16 v[2:17], v[130:133], v[126:129], v[2:17]
	ds_read_b128 v[126:129], v89 offset:34256
	s_waitcnt lgkmcnt(1)
	v_mfma_f32_32x32x16_bf16 v[50:65], v[78:81], v[70:73], v[50:65]
	v_mfma_f32_32x32x16_bf16 v[18:33], v[134:137], v[70:73], v[18:33]
	ds_read_b128 v[70:73], v142 offset:224
	s_waitcnt lgkmcnt(0)
	v_mfma_f32_32x32x16_bf16 v[34:49], v[78:81], v[70:73], v[34:49]
	v_add_u32_e32 v78, 0xdd0, v124
	v_cndmask_b32_e64 v78, v228, v78, s[2:3]
	v_add_u32_e32 v132, v90, v78
	ds_read_b128 v[78:81], v132
	v_add_u32_e32 v124, 0x51d0, v124
	v_mfma_f32_32x32x16_bf16 v[2:17], v[134:137], v[70:73], v[2:17]
	ds_read_b128 v[70:73], v89 offset:34320
	s_waitcnt lgkmcnt(0)
	v_mfma_f32_32x32x16_bf16 v[50:65], v[70:73], v[78:81], v[50:65]
	v_mfma_f32_32x32x16_bf16 v[18:33], v[126:129], v[78:81], v[18:33]
	v_cndmask_b32_e64 v78, v228, v124, s[2:3]
	v_add_u32_e32 v133, v90, v78
	ds_read_b128 v[78:81], v133
	s_movk_i32 s2, 0xfc00
	s_mov_b32 s3, -1
	v_lshl_add_u64 v[82:83], v[82:83], 0, s[2:3]
	v_lshl_add_u64 v[84:85], v[84:85], 0, s[2:3]
	s_waitcnt lgkmcnt(0)
	v_mfma_f32_32x32x16_bf16 v[34:49], v[70:73], v[78:81], v[34:49]
	v_lshl_add_u64 v[86:87], v[86:87], 0, s[2:3]
	v_mfma_f32_32x32x16_bf16 v[2:17], v[126:129], v[78:81], v[2:17]
	ds_read_b128 v[78:81], v89 offset:34352
	ds_read_b128 v[124:127], v132 offset:32
	ds_read_b128 v[128:131], v89 offset:34288
	s_waitcnt lgkmcnt(1)
	v_mfma_f32_32x32x16_bf16 v[50:65], v[78:81], v[124:127], v[50:65]
	s_waitcnt lgkmcnt(0)
	v_mfma_f32_32x32x16_bf16 v[18:33], v[128:131], v[124:127], v[18:33]
	ds_read_b128 v[124:127], v133 offset:32
	s_waitcnt lgkmcnt(0)
	v_mfma_f32_32x32x16_bf16 v[34:49], v[78:81], v[124:127], v[34:49]
	v_mfma_f32_32x32x16_bf16 v[2:17], v[128:131], v[124:127], v[2:17]
	ds_read_b128 v[128:131], v132 offset:64
	ds_read_b128 v[200:203], v133 offset:64
	ds_read_b128 v[124:127], v89 offset:34384
	s_waitcnt lgkmcnt(2)
	v_mfma_f32_32x32x16_bf16 v[18:33], v[70:73], v[128:131], v[18:33]
	s_waitcnt lgkmcnt(1)
	v_mfma_f32_32x32x16_bf16 v[2:17], v[70:73], v[200:203], v[2:17]
	s_waitcnt lgkmcnt(0)
	v_mfma_f32_32x32x16_bf16 v[50:65], v[124:127], v[128:131], v[50:65]
	v_mfma_f32_32x32x16_bf16 v[34:49], v[124:127], v[200:203], v[34:49]
	ds_read_b128 v[128:131], v132 offset:96
	ds_read_b128 v[200:203], v133 offset:96
	ds_read_b128 v[70:73], v89 offset:34416
	s_waitcnt lgkmcnt(2)
	v_mfma_f32_32x32x16_bf16 v[18:33], v[78:81], v[128:131], v[18:33]
	s_waitcnt lgkmcnt(1)
	v_mfma_f32_32x32x16_bf16 v[2:17], v[78:81], v[200:203], v[2:17]
	s_waitcnt lgkmcnt(0)
	v_mfma_f32_32x32x16_bf16 v[50:65], v[70:73], v[128:131], v[50:65]
	v_mfma_f32_32x32x16_bf16 v[34:49], v[70:73], v[200:203], v[34:49]
	ds_read_b128 v[128:131], v132 offset:128
	ds_read_b128 v[200:203], v133 offset:128
	ds_read_b128 v[78:81], v89 offset:34448
	s_waitcnt lgkmcnt(2)
	v_mfma_f32_32x32x16_bf16 v[18:33], v[124:127], v[128:131], v[18:33]
	s_waitcnt lgkmcnt(1)
	v_mfma_f32_32x32x16_bf16 v[2:17], v[124:127], v[200:203], v[2:17]
	s_waitcnt lgkmcnt(0)
	v_mfma_f32_32x32x16_bf16 v[50:65], v[78:81], v[128:131], v[50:65]
	v_mfma_f32_32x32x16_bf16 v[34:49], v[78:81], v[200:203], v[34:49]
	ds_read_b128 v[128:131], v132 offset:160
	ds_read_b128 v[124:127], v89 offset:34480
	s_waitcnt lgkmcnt(1)
	v_mfma_f32_32x32x16_bf16 v[18:33], v[70:73], v[128:131], v[18:33]
	s_waitcnt lgkmcnt(0)
	v_mfma_f32_32x32x16_bf16 v[50:65], v[124:127], v[128:131], v[50:65]
	ds_read_b128 v[128:131], v133 offset:160
	s_waitcnt lgkmcnt(0)
	v_mfma_f32_32x32x16_bf16 v[2:17], v[70:73], v[128:131], v[2:17]
	ds_read_b128 v[70:73], v132 offset:192
	v_mfma_f32_32x32x16_bf16 v[34:49], v[124:127], v[128:131], v[34:49]
	s_waitcnt lgkmcnt(0)
	v_mfma_f32_32x32x16_bf16 v[50:65], v[66:69], v[70:73], v[50:65]
	v_mfma_f32_32x32x16_bf16 v[18:33], v[78:81], v[70:73], v[18:33]
	ds_read_b128 v[70:73], v133 offset:192
	s_waitcnt lgkmcnt(0)
	v_mfma_f32_32x32x16_bf16 v[34:49], v[66:69], v[70:73], v[34:49]
	ds_read_b128 v[66:69], v132 offset:224
	v_mfma_f32_32x32x16_bf16 v[2:17], v[78:81], v[70:73], v[2:17]
	s_waitcnt lgkmcnt(0)
	v_mfma_f32_32x32x16_bf16 v[50:65], v[74:77], v[66:69], v[50:65]
	v_mfma_f32_32x32x16_bf16 v[18:33], v[124:127], v[66:69], v[18:33]
	ds_read_b128 v[66:69], v133 offset:224
	s_waitcnt lgkmcnt(0)
	v_mfma_f32_32x32x16_bf16 v[34:49], v[74:77], v[66:69], v[34:49]
	v_mfma_f32_32x32x16_bf16 v[2:17], v[124:127], v[66:69], v[2:17]
	s_cbranch_scc1 .LBB0_1205

; #define MFMA(a, b, c) __builtin_amdgcn_mfma_f32_32x32x16_bf16((a), (b), (c), 0, 0, 0)
; __device__ __forceinline__ void toeplitz_item(const Params& p, int layer, int half, int c, bf16* sm, int dry, unsigned* done_ctr) {
;     ...
;       } else if (actv[0]) {
; #pragma unroll
;         for (int ks = 0; ks < 8; ++ks) {
;           const s8v a0 = *(const s8v*)(ap0 + 16 * ks), a1 = *(const s8v*)(ap0 - 32 + 16 * ks);
;           const s8v b0 = *(const s8v*)(bp0 + 16 * ks);
;           acc[0][0] = MFMA(a0, b0, acc[0][0]);
;           acc[1][0] = MFMA(a1, b0, acc[1][0]);
;         }
.LBB0_1426:
	s_andn2_saveexec_b64 s[2:3], s[2:3]
	s_cbranch_execz .LBB0_1428
	v_add_u32_e32 v14, v106, v14
	ds_read_b128 v[140:143], v14
	s_waitcnt lgkmcnt(0)
	v_mfma_f32_32x32x16_bf16 v[64:79], v[2:5], v[140:143], v[64:79]
	v_mfma_f32_32x32x16_bf16 v[32:47], v[84:87], v[140:143], v[32:47]
	ds_read_b128 v[84:87], v14 offset:32
	s_waitcnt lgkmcnt(0)
	v_mfma_f32_32x32x16_bf16 v[64:79], v[92:95], v[84:87], v[64:79]
	v_mfma_f32_32x32x16_bf16 v[32:47], v[96:99], v[84:87], v[32:47]
	ds_read_b128 v[84:87], v14 offset:64
	s_waitcnt lgkmcnt(0)
	v_mfma_f32_32x32x16_bf16 v[64:79], v[88:91], v[84:87], v[64:79]
	v_mfma_f32_32x32x16_bf16 v[32:47], v[2:5], v[84:87], v[32:47]
	ds_read_b128 v[2:5], v14 offset:96
	s_waitcnt lgkmcnt(0)
	v_mfma_f32_32x32x16_bf16 v[64:79], v[80:83], v[2:5], v[64:79]
	v_mfma_f32_32x32x16_bf16 v[32:47], v[92:95], v[2:5], v[32:47]
	ds_read_b128 v[2:5], v14 offset:128
	s_waitcnt lgkmcnt(0)
	v_mfma_f32_32x32x16_bf16 v[64:79], v[10:13], v[2:5], v[64:79]
	v_mfma_f32_32x32x16_bf16 v[32:47], v[88:91], v[2:5], v[32:47]
	ds_read_b128 v[2:5], v14 offset:160
	s_waitcnt lgkmcnt(0)
	v_mfma_f32_32x32x16_bf16 v[64:79], v[6:9], v[2:5], v[64:79]
	v_mfma_f32_32x32x16_bf16 v[32:47], v[80:83], v[2:5], v[32:47]
	ds_read_b128 v[80:83], v14 offset:192
	ds_read_b128 v[2:5], v108 offset:35280
	s_waitcnt lgkmcnt(1)
	v_mfma_f32_32x32x16_bf16 v[32:47], v[10:13], v[80:83], v[32:47]
	s_waitcnt lgkmcnt(0)
	v_mfma_f32_32x32x16_bf16 v[64:79], v[2:5], v[80:83], v[64:79]
	ds_read_b128 v[10:13], v14 offset:224
	ds_read_b128 v[2:5], v108 offset:35312
	s_waitcnt lgkmcnt(1)
	v_mfma_f32_32x32x16_bf16 v[32:47], v[6:9], v[10:13], v[32:47]
	s_waitcnt lgkmcnt(0)
	v_mfma_f32_32x32x16_bf16 v[64:79], v[2:5], v[10:13], v[64:79]

; #define MFMA(a, b, c) __builtin_amdgcn_mfma_f32_32x32x16_bf16((a), (b), (c), 0, 0, 0)
; __device__ __forceinline__ void toeplitz_item(const Params& p, int layer, int half, int c, bf16* sm, int dry, unsigned* done_ctr) {
;     ...
;       if (actv[0] && actv[1]) {
; #pragma unroll
;         for (int ks = 0; ks < 8; ++ks) {
;           const s8v a0 = *(const s8v*)(ap0 + 16 * ks), a1 = *(const s8v*)(ap0 - 32 + 16 * ks);
;           const s8v b0 = *(const s8v*)(bp0 + 16 * ks), b1 = *(const s8v*)(bp1 + 16 * ks);
;           acc[0][0] = MFMA(a0, b0, acc[0][0]);
;           acc[1][0] = MFMA(a1, b0, acc[1][0]);
;           acc[0][1] = MFMA(a0, b1, acc[0][1]);
;           acc[1][1] = MFMA(a1, b1, acc[1][1]);
;         }
.LBB0_1429:
	s_andn2_saveexec_b64 s[94:95], s[20:21]
	s_cbranch_execz .LBB0_1431
	v_add_u32_e32 v14, v106, v14
	s_waitcnt lgkmcnt(0)
	ds_read_b128 v[6:9], v14
	v_add_u32_e32 v15, v106, v15
	s_waitcnt lgkmcnt(0)
	v_mfma_f32_32x32x16_bf16 v[64:79], v[2:5], v[6:9], v[64:79]
	v_mfma_f32_32x32x16_bf16 v[32:47], v[84:87], v[6:9], v[32:47]
	ds_read_b128 v[6:9], v15
	s_waitcnt lgkmcnt(0)
	v_mfma_f32_32x32x16_bf16 v[48:63], v[2:5], v[6:9], v[48:63]
	v_mfma_f32_32x32x16_bf16 v[16:31], v[84:87], v[6:9], v[16:31]
	ds_read_b128 v[6:9], v108 offset:35120
	ds_read_b128 v[10:13], v14 offset:32
	ds_read_b128 v[80:83], v108 offset:35056
	s_waitcnt lgkmcnt(1)
	v_mfma_f32_32x32x16_bf16 v[64:79], v[6:9], v[10:13], v[64:79]
	s_waitcnt lgkmcnt(0)
	v_mfma_f32_32x32x16_bf16 v[32:47], v[80:83], v[10:13], v[32:47]
	ds_read_b128 v[10:13], v15 offset:32
	s_waitcnt lgkmcnt(0)
	v_mfma_f32_32x32x16_bf16 v[48:63], v[6:9], v[10:13], v[48:63]
	v_mfma_f32_32x32x16_bf16 v[16:31], v[80:83], v[10:13], v[16:31]
	ds_read_b128 v[80:83], v14 offset:64
	ds_read_b128 v[200:203], v15 offset:64
	ds_read_b128 v[10:13], v108 offset:35152
	s_waitcnt lgkmcnt(2)
	v_mfma_f32_32x32x16_bf16 v[32:47], v[2:5], v[80:83], v[32:47]
	s_waitcnt lgkmcnt(1)
	v_mfma_f32_32x32x16_bf16 v[16:31], v[2:5], v[200:203], v[16:31]
	s_waitcnt lgkmcnt(0)
	v_mfma_f32_32x32x16_bf16 v[64:79], v[10:13], v[80:83], v[64:79]
	v_mfma_f32_32x32x16_bf16 v[48:63], v[10:13], v[200:203], v[48:63]
	ds_read_b128 v[80:83], v14 offset:96
	ds_read_b128 v[200:203], v15 offset:96
	ds_read_b128 v[2:5], v108 offset:35184
	s_waitcnt lgkmcnt(2)
	v_mfma_f32_32x32x16_bf16 v[32:47], v[6:9], v[80:83], v[32:47]
	s_waitcnt lgkmcnt(1)
	v_mfma_f32_32x32x16_bf16 v[16:31], v[6:9], v[200:203], v[16:31]
	s_waitcnt lgkmcnt(0)
	v_mfma_f32_32x32x16_bf16 v[64:79], v[2:5], v[80:83], v[64:79]
	v_mfma_f32_32x32x16_bf16 v[48:63], v[2:5], v[200:203], v[48:63]
	ds_read_b128 v[80:83], v14 offset:128
	ds_read_b128 v[200:203], v15 offset:128
	ds_read_b128 v[6:9], v108 offset:35216
	s_waitcnt lgkmcnt(2)
	v_mfma_f32_32x32x16_bf16 v[32:47], v[10:13], v[80:83], v[32:47]
	s_waitcnt lgkmcnt(1)
	v_mfma_f32_32x32x16_bf16 v[16:31], v[10:13], v[200:203], v[16:31]
	s_waitcnt lgkmcnt(0)
	v_mfma_f32_32x32x16_bf16 v[64:79], v[6:9], v[80:83], v[64:79]
	v_mfma_f32_32x32x16_bf16 v[48:63], v[6:9], v[200:203], v[48:63]
	ds_read_b128 v[80:83], v14 offset:160
	ds_read_b128 v[200:203], v15 offset:160
	ds_read_b128 v[10:13], v108 offset:35248
	s_waitcnt lgkmcnt(2)
	v_mfma_f32_32x32x16_bf16 v[32:47], v[2:5], v[80:83], v[32:47]
	s_waitcnt lgkmcnt(1)
	v_mfma_f32_32x32x16_bf16 v[16:31], v[2:5], v[200:203], v[16:31]
	s_waitcnt lgkmcnt(0)
	v_mfma_f32_32x32x16_bf16 v[64:79], v[10:13], v[80:83], v[64:79]
	v_mfma_f32_32x32x16_bf16 v[48:63], v[10:13], v[200:203], v[48:63]
	ds_read_b128 v[80:83], v14 offset:192
	ds_read_b128 v[2:5], v108 offset:35280
	s_waitcnt lgkmcnt(1)
	v_mfma_f32_32x32x16_bf16 v[32:47], v[6:9], v[80:83], v[32:47]
	s_waitcnt lgkmcnt(0)
	v_mfma_f32_32x32x16_bf16 v[64:79], v[2:5], v[80:83], v[64:79]
	ds_read_b128 v[80:83], v15 offset:192
	s_waitcnt lgkmcnt(0)
	v_mfma_f32_32x32x16_bf16 v[48:63], v[2:5], v[80:83], v[48:63]
	v_mfma_f32_32x32x16_bf16 v[16:31], v[6:9], v[80:83], v[16:31]
	ds_read_b128 v[6:9], v14 offset:224
	ds_read_b128 v[2:5], v108 offset:35312
	s_waitcnt lgkmcnt(1)
	v_mfma_f32_32x32x16_bf16 v[32:47], v[10:13], v[6:9], v[32:47]
	s_waitcnt lgkmcnt(0)
	v_mfma_f32_32x32x16_bf16 v[64:79], v[2:5], v[6:9], v[64:79]
	ds_read_b128 v[6:9], v15 offset:224
	s_waitcnt lgkmcnt(0)
	v_mfma_f32_32x32x16_bf16 v[48:63], v[2:5], v[6:9], v[48:63]
	v_mfma_f32_32x32x16_bf16 v[16:31], v[10:13], v[6:9], v[16:31]

; #define MFMA(a, b, c) __builtin_amdgcn_mfma_f32_32x32x16_bf16((a), (b), (c), 0, 0, 0)
; __device__ __forceinline__ void toeplitz_item(const Params& p, int layer, int half, int c, bf16* sm, int dry, unsigned* done_ctr) {
;     ...
;       } else if (actv[0]) {
; #pragma unroll
;         for (int ks = 0; ks < 8; ++ks) {
;           const s8v a0 = *(const s8v*)(ap0 + 16 * ks), a1 = *(const s8v*)(ap0 - 32 + 16 * ks);
;           const s8v b0 = *(const s8v*)(bp0 + 16 * ks);
;           acc[0][0] = MFMA(a0, b0, acc[0][0]);
;           acc[1][0] = MFMA(a1, b0, acc[1][0]);
;         }
.LBB0_1436:
	s_andn2_saveexec_b64 s[2:3], s[2:3]
	s_cbranch_execz .LBB0_1438
	v_add_u32_e32 v14, v106, v14
	ds_read_b128 v[140:143], v14
	s_waitcnt lgkmcnt(0)
	v_mfma_f32_32x32x16_bf16 v[64:79], v[2:5], v[140:143], v[64:79]
	v_mfma_f32_32x32x16_bf16 v[32:47], v[84:87], v[140:143], v[32:47]
	ds_read_b128 v[84:87], v14 offset:32
	s_waitcnt lgkmcnt(0)
	v_mfma_f32_32x32x16_bf16 v[64:79], v[92:95], v[84:87], v[64:79]
	v_mfma_f32_32x32x16_bf16 v[32:47], v[96:99], v[84:87], v[32:47]
	ds_read_b128 v[84:87], v14 offset:64
	s_waitcnt lgkmcnt(0)
	v_mfma_f32_32x32x16_bf16 v[64:79], v[88:91], v[84:87], v[64:79]
	v_mfma_f32_32x32x16_bf16 v[32:47], v[2:5], v[84:87], v[32:47]
	ds_read_b128 v[2:5], v14 offset:96
	s_waitcnt lgkmcnt(0)
	v_mfma_f32_32x32x16_bf16 v[64:79], v[80:83], v[2:5], v[64:79]
	v_mfma_f32_32x32x16_bf16 v[32:47], v[92:95], v[2:5], v[32:47]
	ds_read_b128 v[2:5], v14 offset:128
	s_waitcnt lgkmcnt(0)
	v_mfma_f32_32x32x16_bf16 v[64:79], v[10:13], v[2:5], v[64:79]
	v_mfma_f32_32x32x16_bf16 v[32:47], v[88:91], v[2:5], v[32:47]
	ds_read_b128 v[2:5], v14 offset:160
	s_waitcnt lgkmcnt(0)
	v_mfma_f32_32x32x16_bf16 v[64:79], v[6:9], v[2:5], v[64:79]
	v_mfma_f32_32x32x16_bf16 v[32:47], v[80:83], v[2:5], v[32:47]
	ds_read_b128 v[80:83], v14 offset:192
	ds_read_b128 v[2:5], v108 offset:35024
	s_waitcnt lgkmcnt(1)
	v_mfma_f32_32x32x16_bf16 v[32:47], v[10:13], v[80:83], v[32:47]
	s_waitcnt lgkmcnt(0)
	v_mfma_f32_32x32x16_bf16 v[64:79], v[2:5], v[80:83], v[64:79]
	ds_read_b128 v[10:13], v14 offset:224
	ds_read_b128 v[2:5], v108 offset:35056
	s_waitcnt lgkmcnt(1)
	v_mfma_f32_32x32x16_bf16 v[32:47], v[6:9], v[10:13], v[32:47]
	s_waitcnt lgkmcnt(0)
	v_mfma_f32_32x32x16_bf16 v[64:79], v[2:5], v[10:13], v[64:79]

; #define MFMA(a, b, c) __builtin_amdgcn_mfma_f32_32x32x16_bf16((a), (b), (c), 0, 0, 0)
; __device__ __forceinline__ void toeplitz_item(const Params& p, int layer, int half, int c, bf16* sm, int dry, unsigned* done_ctr) {
;     ...
;       if (actv[0] && actv[1]) {
; #pragma unroll
;         for (int ks = 0; ks < 8; ++ks) {
;           const s8v a0 = *(const s8v*)(ap0 + 16 * ks), a1 = *(const s8v*)(ap0 - 32 + 16 * ks);
;           const s8v b0 = *(const s8v*)(bp0 + 16 * ks), b1 = *(const s8v*)(bp1 + 16 * ks);
;           acc[0][0] = MFMA(a0, b0, acc[0][0]);
;           acc[1][0] = MFMA(a1, b0, acc[1][0]);
;           acc[0][1] = MFMA(a0, b1, acc[0][1]);
;           acc[1][1] = MFMA(a1, b1, acc[1][1]);
;         }
.LBB0_1439:
	s_andn2_saveexec_b64 s[20:21], s[20:21]
	s_cbranch_execz .LBB0_1441
	v_add_u32_e32 v14, v106, v14
	s_waitcnt lgkmcnt(0)
	ds_read_b128 v[6:9], v14
	v_add_u32_e32 v15, v106, v15
	s_waitcnt lgkmcnt(0)
	v_mfma_f32_32x32x16_bf16 v[64:79], v[2:5], v[6:9], v[64:79]
	v_mfma_f32_32x32x16_bf16 v[32:47], v[84:87], v[6:9], v[32:47]
	ds_read_b128 v[6:9], v15
	s_waitcnt lgkmcnt(0)
	v_mfma_f32_32x32x16_bf16 v[48:63], v[2:5], v[6:9], v[48:63]
	v_mfma_f32_32x32x16_bf16 v[16:31], v[84:87], v[6:9], v[16:31]
	ds_read_b128 v[6:9], v108 offset:34864
	ds_read_b128 v[10:13], v14 offset:32
	ds_read_b128 v[80:83], v108 offset:34800
	s_waitcnt lgkmcnt(1)
	v_mfma_f32_32x32x16_bf16 v[64:79], v[6:9], v[10:13], v[64:79]
	s_waitcnt lgkmcnt(0)
	v_mfma_f32_32x32x16_bf16 v[32:47], v[80:83], v[10:13], v[32:47]
	ds_read_b128 v[10:13], v15 offset:32
	s_waitcnt lgkmcnt(0)
	v_mfma_f32_32x32x16_bf16 v[48:63], v[6:9], v[10:13], v[48:63]
	v_mfma_f32_32x32x16_bf16 v[16:31], v[80:83], v[10:13], v[16:31]
	ds_read_b128 v[80:83], v14 offset:64
	ds_read_b128 v[200:203], v15 offset:64
	ds_read_b128 v[10:13], v108 offset:34896
	s_waitcnt lgkmcnt(2)
	v_mfma_f32_32x32x16_bf16 v[32:47], v[2:5], v[80:83], v[32:47]
	s_waitcnt lgkmcnt(1)
	v_mfma_f32_32x32x16_bf16 v[16:31], v[2:5], v[200:203], v[16:31]
	s_waitcnt lgkmcnt(0)
	v_mfma_f32_32x32x16_bf16 v[64:79], v[10:13], v[80:83], v[64:79]
	v_mfma_f32_32x32x16_bf16 v[48:63], v[10:13], v[200:203], v[48:63]
	ds_read_b128 v[80:83], v14 offset:96
	ds_read_b128 v[200:203], v15 offset:96
	ds_read_b128 v[2:5], v108 offset:34928
	s_waitcnt lgkmcnt(2)
	v_mfma_f32_32x32x16_bf16 v[32:47], v[6:9], v[80:83], v[32:47]
	s_waitcnt lgkmcnt(1)
	v_mfma_f32_32x32x16_bf16 v[16:31], v[6:9], v[200:203], v[16:31]
	s_waitcnt lgkmcnt(0)
	v_mfma_f32_32x32x16_bf16 v[64:79], v[2:5], v[80:83], v[64:79]
	v_mfma_f32_32x32x16_bf16 v[48:63], v[2:5], v[200:203], v[48:63]
	ds_read_b128 v[80:83], v14 offset:128
	ds_read_b128 v[200:203], v15 offset:128
	ds_read_b128 v[6:9], v108 offset:34960
	s_waitcnt lgkmcnt(2)
	v_mfma_f32_32x32x16_bf16 v[32:47], v[10:13], v[80:83], v[32:47]
	s_waitcnt lgkmcnt(1)
	v_mfma_f32_32x32x16_bf16 v[16:31], v[10:13], v[200:203], v[16:31]
	s_waitcnt lgkmcnt(0)
	v_mfma_f32_32x32x16_bf16 v[64:79], v[6:9], v[80:83], v[64:79]
	v_mfma_f32_32x32x16_bf16 v[48:63], v[6:9], v[200:203], v[48:63]
	ds_read_b128 v[80:83], v14 offset:160
	ds_read_b128 v[200:203], v15 offset:160
	ds_read_b128 v[10:13], v108 offset:34992
	s_waitcnt lgkmcnt(2)
	v_mfma_f32_32x32x16_bf16 v[32:47], v[2:5], v[80:83], v[32:47]
	s_waitcnt lgkmcnt(1)
	v_mfma_f32_32x32x16_bf16 v[16:31], v[2:5], v[200:203], v[16:31]
	s_waitcnt lgkmcnt(0)
	v_mfma_f32_32x32x16_bf16 v[64:79], v[10:13], v[80:83], v[64:79]
	v_mfma_f32_32x32x16_bf16 v[48:63], v[10:13], v[200:203], v[48:63]
	ds_read_b128 v[80:83], v14 offset:192
	ds_read_b128 v[2:5], v108 offset:35024
	s_waitcnt lgkmcnt(1)
	v_mfma_f32_32x32x16_bf16 v[32:47], v[6:9], v[80:83], v[32:47]
	s_waitcnt lgkmcnt(0)
	v_mfma_f32_32x32x16_bf16 v[64:79], v[2:5], v[80:83], v[64:79]
	ds_read_b128 v[80:83], v15 offset:192
	s_waitcnt lgkmcnt(0)
	v_mfma_f32_32x32x16_bf16 v[48:63], v[2:5], v[80:83], v[48:63]
	v_mfma_f32_32x32x16_bf16 v[16:31], v[6:9], v[80:83], v[16:31]
	ds_read_b128 v[6:9], v14 offset:224
	ds_read_b128 v[2:5], v108 offset:35056
	s_waitcnt lgkmcnt(1)
	v_mfma_f32_32x32x16_bf16 v[32:47], v[10:13], v[6:9], v[32:47]
	s_waitcnt lgkmcnt(0)
	v_mfma_f32_32x32x16_bf16 v[64:79], v[2:5], v[6:9], v[64:79]
	ds_read_b128 v[6:9], v15 offset:224
	s_waitcnt lgkmcnt(0)
	v_mfma_f32_32x32x16_bf16 v[48:63], v[2:5], v[6:9], v[48:63]
	v_mfma_f32_32x32x16_bf16 v[16:31], v[10:13], v[6:9], v[16:31]

; #define MFMA(a, b, c) __builtin_amdgcn_mfma_f32_32x32x16_bf16((a), (b), (c), 0, 0, 0)
; __device__ __forceinline__ void toeplitz_item(const Params& p, int layer, int half, int c, bf16* sm, int dry, unsigned* done_ctr) {
;     ...
;       } else if (actv[0]) {
; #pragma unroll
;         for (int ks = 0; ks < 8; ++ks) {
;           const s8v a0 = *(const s8v*)(ap0 + 16 * ks), a1 = *(const s8v*)(ap0 - 32 + 16 * ks);
;           const s8v b0 = *(const s8v*)(bp0 + 16 * ks);
;           acc[0][0] = MFMA(a0, b0, acc[0][0]);
;           acc[1][0] = MFMA(a1, b0, acc[1][0]);
;         }
.LBB0_1446:
	s_andn2_saveexec_b64 s[2:3], s[2:3]
	s_cbranch_execz .LBB0_1448
	v_add_u32_e32 v14, v106, v14
	ds_read_b128 v[140:143], v14
	s_waitcnt lgkmcnt(0)
	v_mfma_f32_32x32x16_bf16 v[64:79], v[2:5], v[140:143], v[64:79]
	v_mfma_f32_32x32x16_bf16 v[32:47], v[84:87], v[140:143], v[32:47]
	ds_read_b128 v[84:87], v14 offset:32
	s_waitcnt lgkmcnt(0)
	v_mfma_f32_32x32x16_bf16 v[64:79], v[92:95], v[84:87], v[64:79]
	v_mfma_f32_32x32x16_bf16 v[32:47], v[96:99], v[84:87], v[32:47]
	ds_read_b128 v[84:87], v14 offset:64
	s_waitcnt lgkmcnt(0)
	v_mfma_f32_32x32x16_bf16 v[64:79], v[88:91], v[84:87], v[64:79]
	v_mfma_f32_32x32x16_bf16 v[32:47], v[2:5], v[84:87], v[32:47]
	ds_read_b128 v[2:5], v14 offset:96
	s_waitcnt lgkmcnt(0)
	v_mfma_f32_32x32x16_bf16 v[64:79], v[80:83], v[2:5], v[64:79]
	v_mfma_f32_32x32x16_bf16 v[32:47], v[92:95], v[2:5], v[32:47]
	ds_read_b128 v[2:5], v14 offset:128
	s_waitcnt lgkmcnt(0)
	v_mfma_f32_32x32x16_bf16 v[64:79], v[10:13], v[2:5], v[64:79]
	v_mfma_f32_32x32x16_bf16 v[32:47], v[88:91], v[2:5], v[32:47]
	ds_read_b128 v[2:5], v14 offset:160
	s_waitcnt lgkmcnt(0)
	v_mfma_f32_32x32x16_bf16 v[64:79], v[6:9], v[2:5], v[64:79]
	v_mfma_f32_32x32x16_bf16 v[32:47], v[80:83], v[2:5], v[32:47]
	ds_read_b128 v[80:83], v14 offset:192
	ds_read_b128 v[2:5], v108 offset:34768
	s_waitcnt lgkmcnt(1)
	v_mfma_f32_32x32x16_bf16 v[32:47], v[10:13], v[80:83], v[32:47]
	s_waitcnt lgkmcnt(0)
	v_mfma_f32_32x32x16_bf16 v[64:79], v[2:5], v[80:83], v[64:79]
	ds_read_b128 v[10:13], v14 offset:224
	ds_read_b128 v[2:5], v108 offset:34800
	s_waitcnt lgkmcnt(1)
	v_mfma_f32_32x32x16_bf16 v[32:47], v[6:9], v[10:13], v[32:47]
	s_waitcnt lgkmcnt(0)
	v_mfma_f32_32x32x16_bf16 v[64:79], v[2:5], v[10:13], v[64:79]

; #define MFMA(a, b, c) __builtin_amdgcn_mfma_f32_32x32x16_bf16((a), (b), (c), 0, 0, 0)
; __device__ __forceinline__ void toeplitz_item(const Params& p, int layer, int half, int c, bf16* sm, int dry, unsigned* done_ctr) {
;     ...
;       if (actv[0] && actv[1]) {
; #pragma unroll
;         for (int ks = 0; ks < 8; ++ks) {
;           const s8v a0 = *(const s8v*)(ap0 + 16 * ks), a1 = *(const s8v*)(ap0 - 32 + 16 * ks);
;           const s8v b0 = *(const s8v*)(bp0 + 16 * ks), b1 = *(const s8v*)(bp1 + 16 * ks);
;           acc[0][0] = MFMA(a0, b0, acc[0][0]);
;           acc[1][0] = MFMA(a1, b0, acc[1][0]);
;           acc[0][1] = MFMA(a0, b1, acc[0][1]);
;           acc[1][1] = MFMA(a1, b1, acc[1][1]);
;         }
.LBB0_1449:
	s_andn2_saveexec_b64 s[20:21], s[20:21]
	s_cbranch_execz .LBB0_1451
	v_add_u32_e32 v14, v106, v14
	s_waitcnt lgkmcnt(0)
	ds_read_b128 v[6:9], v14
	v_add_u32_e32 v15, v106, v15
	s_waitcnt lgkmcnt(0)
	v_mfma_f32_32x32x16_bf16 v[64:79], v[2:5], v[6:9], v[64:79]
	v_mfma_f32_32x32x16_bf16 v[32:47], v[84:87], v[6:9], v[32:47]
	ds_read_b128 v[6:9], v15
	s_waitcnt lgkmcnt(0)
	v_mfma_f32_32x32x16_bf16 v[48:63], v[2:5], v[6:9], v[48:63]
	v_mfma_f32_32x32x16_bf16 v[16:31], v[84:87], v[6:9], v[16:31]
	ds_read_b128 v[6:9], v108 offset:34608
	ds_read_b128 v[10:13], v14 offset:32
	ds_read_b128 v[80:83], v108 offset:34544
	s_waitcnt lgkmcnt(1)
	v_mfma_f32_32x32x16_bf16 v[64:79], v[6:9], v[10:13], v[64:79]
	s_waitcnt lgkmcnt(0)
	v_mfma_f32_32x32x16_bf16 v[32:47], v[80:83], v[10:13], v[32:47]
	ds_read_b128 v[10:13], v15 offset:32
	s_waitcnt lgkmcnt(0)
	v_mfma_f32_32x32x16_bf16 v[48:63], v[6:9], v[10:13], v[48:63]
	v_mfma_f32_32x32x16_bf16 v[16:31], v[80:83], v[10:13], v[16:31]
	ds_read_b128 v[80:83], v14 offset:64
	ds_read_b128 v[200:203], v15 offset:64
	ds_read_b128 v[10:13], v108 offset:34640
	s_waitcnt lgkmcnt(2)
	v_mfma_f32_32x32x16_bf16 v[32:47], v[2:5], v[80:83], v[32:47]
	s_waitcnt lgkmcnt(1)
	v_mfma_f32_32x32x16_bf16 v[16:31], v[2:5], v[200:203], v[16:31]
	s_waitcnt lgkmcnt(0)
	v_mfma_f32_32x32x16_bf16 v[64:79], v[10:13], v[80:83], v[64:79]
	v_mfma_f32_32x32x16_bf16 v[48:63], v[10:13], v[200:203], v[48:63]
	ds_read_b128 v[80:83], v14 offset:96
	ds_read_b128 v[200:203], v15 offset:96
	ds_read_b128 v[2:5], v108 offset:34672
	s_waitcnt lgkmcnt(2)
	v_mfma_f32_32x32x16_bf16 v[32:47], v[6:9], v[80:83], v[32:47]
	s_waitcnt lgkmcnt(1)
	v_mfma_f32_32x32x16_bf16 v[16:31], v[6:9], v[200:203], v[16:31]
	s_waitcnt lgkmcnt(0)
	v_mfma_f32_32x32x16_bf16 v[64:79], v[2:5], v[80:83], v[64:79]
	v_mfma_f32_32x32x16_bf16 v[48:63], v[2:5], v[200:203], v[48:63]
	ds_read_b128 v[80:83], v14 offset:128
	ds_read_b128 v[200:203], v15 offset:128
	ds_read_b128 v[6:9], v108 offset:34704
	s_waitcnt lgkmcnt(2)
	v_mfma_f32_32x32x16_bf16 v[32:47], v[10:13], v[80:83], v[32:47]
	s_waitcnt lgkmcnt(1)
	v_mfma_f32_32x32x16_bf16 v[16:31], v[10:13], v[200:203], v[16:31]
	s_waitcnt lgkmcnt(0)
	v_mfma_f32_32x32x16_bf16 v[64:79], v[6:9], v[80:83], v[64:79]
	v_mfma_f32_32x32x16_bf16 v[48:63], v[6:9], v[200:203], v[48:63]
	ds_read_b128 v[80:83], v14 offset:160
	ds_read_b128 v[200:203], v15 offset:160
	ds_read_b128 v[10:13], v108 offset:34736
	s_waitcnt lgkmcnt(2)
	v_mfma_f32_32x32x16_bf16 v[32:47], v[2:5], v[80:83], v[32:47]
	s_waitcnt lgkmcnt(1)
	v_mfma_f32_32x32x16_bf16 v[16:31], v[2:5], v[200:203], v[16:31]
	s_waitcnt lgkmcnt(0)
	v_mfma_f32_32x32x16_bf16 v[64:79], v[10:13], v[80:83], v[64:79]
	v_mfma_f32_32x32x16_bf16 v[48:63], v[10:13], v[200:203], v[48:63]
	ds_read_b128 v[80:83], v14 offset:192
	ds_read_b128 v[2:5], v108 offset:34768
	s_waitcnt lgkmcnt(1)
	v_mfma_f32_32x32x16_bf16 v[32:47], v[6:9], v[80:83], v[32:47]
	s_waitcnt lgkmcnt(0)
	v_mfma_f32_32x32x16_bf16 v[64:79], v[2:5], v[80:83], v[64:79]
	ds_read_b128 v[80:83], v15 offset:192
	s_waitcnt lgkmcnt(0)
	v_mfma_f32_32x32x16_bf16 v[48:63], v[2:5], v[80:83], v[48:63]
	v_mfma_f32_32x32x16_bf16 v[16:31], v[6:9], v[80:83], v[16:31]
	ds_read_b128 v[6:9], v14 offset:224
	ds_read_b128 v[2:5], v108 offset:34800
	s_waitcnt lgkmcnt(1)
	v_mfma_f32_32x32x16_bf16 v[32:47], v[10:13], v[6:9], v[32:47]
	s_waitcnt lgkmcnt(0)
	v_mfma_f32_32x32x16_bf16 v[64:79], v[2:5], v[6:9], v[64:79]
	ds_read_b128 v[6:9], v15 offset:224
	s_waitcnt lgkmcnt(0)
	v_mfma_f32_32x32x16_bf16 v[48:63], v[2:5], v[6:9], v[48:63]
	v_mfma_f32_32x32x16_bf16 v[16:31], v[10:13], v[6:9], v[16:31]

; #define MFMA(a, b, c) __builtin_amdgcn_mfma_f32_32x32x16_bf16((a), (b), (c), 0, 0, 0)
; __device__ __forceinline__ void toeplitz_item(const Params& p, int layer, int half, int c, bf16* sm, int dry, unsigned* done_ctr) {
;     ...
;       } else if (actv[0]) {
; #pragma unroll
;         for (int ks = 0; ks < 8; ++ks) {
;           const s8v a0 = *(const s8v*)(ap0 + 16 * ks), a1 = *(const s8v*)(ap0 - 32 + 16 * ks);
;           const s8v b0 = *(const s8v*)(bp0 + 16 * ks);
;           acc[0][0] = MFMA(a0, b0, acc[0][0]);
;           acc[1][0] = MFMA(a1, b0, acc[1][0]);
;         }
.LBB0_1456:
	s_andn2_saveexec_b64 s[2:3], s[2:3]
	s_cbranch_execz .LBB0_1458
	v_add_u32_e32 v0, v106, v0
	ds_read_b128 v[140:143], v0
	s_waitcnt lgkmcnt(0)
	v_mfma_f32_32x32x16_bf16 v[64:79], v[2:5], v[140:143], v[64:79]
	v_mfma_f32_32x32x16_bf16 v[32:47], v[84:87], v[140:143], v[32:47]
	ds_read_b128 v[84:87], v0 offset:32
	s_waitcnt lgkmcnt(0)
	v_mfma_f32_32x32x16_bf16 v[64:79], v[92:95], v[84:87], v[64:79]
	v_mfma_f32_32x32x16_bf16 v[32:47], v[96:99], v[84:87], v[32:47]
	ds_read_b128 v[84:87], v0 offset:64
	s_waitcnt lgkmcnt(0)
	v_mfma_f32_32x32x16_bf16 v[64:79], v[88:91], v[84:87], v[64:79]
	v_mfma_f32_32x32x16_bf16 v[32:47], v[2:5], v[84:87], v[32:47]
	ds_read_b128 v[2:5], v0 offset:96
	s_waitcnt lgkmcnt(0)
	v_mfma_f32_32x32x16_bf16 v[64:79], v[80:83], v[2:5], v[64:79]
	v_mfma_f32_32x32x16_bf16 v[32:47], v[92:95], v[2:5], v[32:47]
	ds_read_b128 v[2:5], v0 offset:128
	s_waitcnt lgkmcnt(0)
	v_mfma_f32_32x32x16_bf16 v[64:79], v[10:13], v[2:5], v[64:79]
	v_mfma_f32_32x32x16_bf16 v[32:47], v[88:91], v[2:5], v[32:47]
	ds_read_b128 v[2:5], v0 offset:160
	s_waitcnt lgkmcnt(0)
	v_mfma_f32_32x32x16_bf16 v[64:79], v[6:9], v[2:5], v[64:79]
	v_mfma_f32_32x32x16_bf16 v[32:47], v[80:83], v[2:5], v[32:47]
	ds_read_b128 v[80:83], v0 offset:192
	ds_read_b128 v[2:5], v108 offset:34512
	s_waitcnt lgkmcnt(1)
	v_mfma_f32_32x32x16_bf16 v[32:47], v[10:13], v[80:83], v[32:47]
	s_waitcnt lgkmcnt(0)
	v_mfma_f32_32x32x16_bf16 v[64:79], v[2:5], v[80:83], v[64:79]
	ds_read_b128 v[10:13], v0 offset:224
	ds_read_b128 v[2:5], v108 offset:34544
	s_waitcnt lgkmcnt(1)
	v_mfma_f32_32x32x16_bf16 v[32:47], v[6:9], v[10:13], v[32:47]
	s_waitcnt lgkmcnt(0)
	v_mfma_f32_32x32x16_bf16 v[64:79], v[2:5], v[10:13], v[64:79]

; #define MFMA(a, b, c) __builtin_amdgcn_mfma_f32_32x32x16_bf16((a), (b), (c), 0, 0, 0)
; __device__ __forceinline__ void toeplitz_item(const Params& p, int layer, int half, int c, bf16* sm, int dry, unsigned* done_ctr) {
;     ...
;       if (actv[0] && actv[1]) {
; #pragma unroll
;         for (int ks = 0; ks < 8; ++ks) {
;           const s8v a0 = *(const s8v*)(ap0 + 16 * ks), a1 = *(const s8v*)(ap0 - 32 + 16 * ks);
;           const s8v b0 = *(const s8v*)(bp0 + 16 * ks), b1 = *(const s8v*)(bp1 + 16 * ks);
;           acc[0][0] = MFMA(a0, b0, acc[0][0]);
;           acc[1][0] = MFMA(a1, b0, acc[1][0]);
;           acc[0][1] = MFMA(a0, b1, acc[0][1]);
;           acc[1][1] = MFMA(a1, b1, acc[1][1]);
;         }
.LBB0_1459:
	s_andn2_saveexec_b64 s[20:21], s[20:21]
	s_cbranch_execz .LBB0_1369
	v_add_u32_e32 v0, v106, v0
	s_waitcnt lgkmcnt(0)
	ds_read_b128 v[6:9], v0
	v_add_u32_e32 v14, v106, v14
	s_waitcnt lgkmcnt(0)
	v_mfma_f32_32x32x16_bf16 v[64:79], v[2:5], v[6:9], v[64:79]
	v_mfma_f32_32x32x16_bf16 v[32:47], v[84:87], v[6:9], v[32:47]
	ds_read_b128 v[6:9], v14
	s_waitcnt lgkmcnt(0)
	v_mfma_f32_32x32x16_bf16 v[48:63], v[2:5], v[6:9], v[48:63]
	v_mfma_f32_32x32x16_bf16 v[16:31], v[84:87], v[6:9], v[16:31]
	ds_read_b128 v[6:9], v108 offset:34352
	ds_read_b128 v[10:13], v0 offset:32
	ds_read_b128 v[80:83], v108 offset:34288
	s_waitcnt lgkmcnt(1)
	v_mfma_f32_32x32x16_bf16 v[64:79], v[6:9], v[10:13], v[64:79]
	s_waitcnt lgkmcnt(0)
	v_mfma_f32_32x32x16_bf16 v[32:47], v[80:83], v[10:13], v[32:47]
	ds_read_b128 v[10:13], v14 offset:32
	s_waitcnt lgkmcnt(0)
	v_mfma_f32_32x32x16_bf16 v[48:63], v[6:9], v[10:13], v[48:63]
	v_mfma_f32_32x32x16_bf16 v[16:31], v[80:83], v[10:13], v[16:31]
	ds_read_b128 v[80:83], v0 offset:64
	ds_read_b128 v[200:203], v14 offset:64
	ds_read_b128 v[10:13], v108 offset:34384
	s_waitcnt lgkmcnt(2)
	v_mfma_f32_32x32x16_bf16 v[32:47], v[2:5], v[80:83], v[32:47]
	s_waitcnt lgkmcnt(1)
	v_mfma_f32_32x32x16_bf16 v[16:31], v[2:5], v[200:203], v[16:31]
	s_waitcnt lgkmcnt(0)
	v_mfma_f32_32x32x16_bf16 v[64:79], v[10:13], v[80:83], v[64:79]
	v_mfma_f32_32x32x16_bf16 v[48:63], v[10:13], v[200:203], v[48:63]
	ds_read_b128 v[80:83], v0 offset:96
	ds_read_b128 v[200:203], v14 offset:96
	ds_read_b128 v[2:5], v108 offset:34416
	s_waitcnt lgkmcnt(2)
	v_mfma_f32_32x32x16_bf16 v[32:47], v[6:9], v[80:83], v[32:47]
	s_waitcnt lgkmcnt(1)
	v_mfma_f32_32x32x16_bf16 v[16:31], v[6:9], v[200:203], v[16:31]
	s_waitcnt lgkmcnt(0)
	v_mfma_f32_32x32x16_bf16 v[64:79], v[2:5], v[80:83], v[64:79]
	v_mfma_f32_32x32x16_bf16 v[48:63], v[2:5], v[200:203], v[48:63]
	ds_read_b128 v[80:83], v0 offset:128
	ds_read_b128 v[200:203], v14 offset:128
	ds_read_b128 v[6:9], v108 offset:34448
	s_waitcnt lgkmcnt(2)
	v_mfma_f32_32x32x16_bf16 v[32:47], v[10:13], v[80:83], v[32:47]
	s_waitcnt lgkmcnt(1)
	v_mfma_f32_32x32x16_bf16 v[16:31], v[10:13], v[200:203], v[16:31]
	s_waitcnt lgkmcnt(0)
	v_mfma_f32_32x32x16_bf16 v[64:79], v[6:9], v[80:83], v[64:79]
	v_mfma_f32_32x32x16_bf16 v[48:63], v[6:9], v[200:203], v[48:63]
	ds_read_b128 v[80:83], v0 offset:160
	ds_read_b128 v[200:203], v14 offset:160
	ds_read_b128 v[10:13], v108 offset:34480
	s_waitcnt lgkmcnt(2)
	v_mfma_f32_32x32x16_bf16 v[32:47], v[2:5], v[80:83], v[32:47]
	s_waitcnt lgkmcnt(1)
	v_mfma_f32_32x32x16_bf16 v[16:31], v[2:5], v[200:203], v[16:31]
	s_waitcnt lgkmcnt(0)
	v_mfma_f32_32x32x16_bf16 v[64:79], v[10:13], v[80:83], v[64:79]
	v_mfma_f32_32x32x16_bf16 v[48:63], v[10:13], v[200:203], v[48:63]
	ds_read_b128 v[80:83], v0 offset:192
	ds_read_b128 v[2:5], v108 offset:34512
	s_waitcnt lgkmcnt(1)
	v_mfma_f32_32x32x16_bf16 v[32:47], v[6:9], v[80:83], v[32:47]
	s_waitcnt lgkmcnt(0)
	v_mfma_f32_32x32x16_bf16 v[64:79], v[2:5], v[80:83], v[64:79]
	ds_read_b128 v[80:83], v14 offset:192
	s_waitcnt lgkmcnt(0)
	v_mfma_f32_32x32x16_bf16 v[48:63], v[2:5], v[80:83], v[48:63]
	v_mfma_f32_32x32x16_bf16 v[16:31], v[6:9], v[80:83], v[16:31]
	ds_read_b128 v[6:9], v0 offset:224
	ds_read_b128 v[2:5], v108 offset:34544
	s_waitcnt lgkmcnt(1)
	v_mfma_f32_32x32x16_bf16 v[32:47], v[10:13], v[6:9], v[32:47]
	s_waitcnt lgkmcnt(0)
	v_mfma_f32_32x32x16_bf16 v[64:79], v[2:5], v[6:9], v[64:79]
	ds_read_b128 v[6:9], v14 offset:224
	s_waitcnt lgkmcnt(0)
	v_mfma_f32_32x32x16_bf16 v[48:63], v[2:5], v[6:9], v[48:63]
	v_mfma_f32_32x32x16_bf16 v[16:31], v[10:13], v[6:9], v[16:31]
	s_branch .LBB0_1369

; #define MFMA(a, b, c) __builtin_amdgcn_mfma_f32_32x32x16_bf16((a), (b), (c), 0, 0, 0)
; __device__ __forceinline__ void toeplitz_item(const Params& p, int layer, int half, int c, bf16* sm, int dry, unsigned* done_ctr) {
;     ...
;       for (int ni = 0; ni < 2; ++ni) {
;         const int nlo = 32 * wn + 64 * ni;
;         actv[ni] = half ? true : !((nlo + 31 - D < 0) || (nlo - D >= 128));
;         const int n = nlo + r;
;         const int src = n - D;
;         const bool valid = half ? ((unsigned)((n & 15) - D) < 16u) : ((unsigned)src < 128u);
;         bblk[ni] = valid ? src : 128;
;       }
;       if (!actv[0] && !actv[1]) continue;
;       const int tb = 16 * (3 - Dl) + 16 + hh - rt;
;       const bf16* ap0 = sW + (aq * 83 + tb - 4 * (2 * wm)) * 8;
;       const bf16* bp0 = sU + bblk[0] * 136 + 8 * hh;
;       const bf16* bp1 = sU + bblk[1] * 136 + 8 * hh;
;       if (actv[0] && actv[1]) {
; #pragma unroll
;         for (int ks = 0; ks < 8; ++ks) {
;           const s8v a0 = *(const s8v*)(ap0 + 16 * ks), a1 = *(const s8v*)(ap0 - 32 + 16 * ks);
;           const s8v b0 = *(const s8v*)(bp0 + 16 * ks), b1 = *(const s8v*)(bp1 + 16 * ks);
;           acc[0][0] = MFMA(a0, b0, acc[0][0]);
;           acc[1][0] = MFMA(a1, b0, acc[1][0]);
;           acc[0][1] = MFMA(a0, b1, acc[0][1]);
;           acc[1][1] = MFMA(a1, b1, acc[1][1]);
;         }
;       } else if (actv[0]) {
; #pragma unroll
;         for (int ks = 0; ks < 8; ++ks) {
;           const s8v a0 = *(const s8v*)(ap0 + 16 * ks), a1 = *(const s8v*)(ap0 - 32 + 16 * ks);
;           const s8v b0 = *(const s8v*)(bp0 + 16 * ks);
;           acc[0][0] = MFMA(a0, b0, acc[0][0]);
;           acc[1][0] = MFMA(a1, b0, acc[1][0]);
;         }
;       } else {
; #pragma unroll
;         for (int ks = 0; ks < 8; ++ks) {
;           const s8v a0 = *(const s8v*)(ap0 + 16 * ks), a1 = *(const s8v*)(ap0 - 32 + 16 * ks);
;           const s8v b1 = *(const s8v*)(bp1 + 16 * ks);
;           acc[0][1] = MFMA(a0, b1, acc[0][1]);
;           acc[1][1] = MFMA(a1, b1, acc[1][1]);
;         }
.LBB0_1514:
	s_or_b64 exec, exec, s[2:3]
	s_movk_i32 s0, 0x7b
	v_cmp_lt_u32_e32 vcc, s0, v109
	s_waitcnt lgkmcnt(0)
	s_barrier
	s_and_saveexec_b64 s[2:3], vcc
	s_cbranch_execz .LBB0_1516
	v_subrev_u32_e32 v0, 60, v105
	v_min_u32_e32 v0, 0x80, v0
	s_movk_i32 s0, 0x110
	v_mad_u32_u24 v0, v0, s0, v106
	ds_read_b128 v[2:5], v108 offset:35088
	ds_read_b128 v[6:9], v0
	ds_read_b128 v[10:13], v108 offset:35024
	s_waitcnt lgkmcnt(1)
	v_mfma_f32_32x32x16_bf16 v[48:63], v[2:5], v[6:9], v[48:63]
	s_waitcnt lgkmcnt(0)
	v_mfma_f32_32x32x16_bf16 v[16:31], v[10:13], v[6:9], v[16:31]
	ds_read_b128 v[6:9], v108 offset:35120
	ds_read_b128 v[10:13], v0 offset:32
	ds_read_b128 v[80:83], v108 offset:35056
	s_waitcnt lgkmcnt(1)
	v_mfma_f32_32x32x16_bf16 v[48:63], v[6:9], v[10:13], v[48:63]
	s_waitcnt lgkmcnt(0)
	v_mfma_f32_32x32x16_bf16 v[16:31], v[80:83], v[10:13], v[16:31]
	ds_read_b128 v[80:83], v0 offset:64
	ds_read_b128 v[10:13], v108 offset:35152
	s_waitcnt lgkmcnt(1)
	v_mfma_f32_32x32x16_bf16 v[16:31], v[2:5], v[80:83], v[16:31]
	s_waitcnt lgkmcnt(0)
	v_mfma_f32_32x32x16_bf16 v[48:63], v[10:13], v[80:83], v[48:63]
	ds_read_b128 v[80:83], v0 offset:96
	ds_read_b128 v[2:5], v108 offset:35184
	s_waitcnt lgkmcnt(1)
	v_mfma_f32_32x32x16_bf16 v[16:31], v[6:9], v[80:83], v[16:31]
	s_waitcnt lgkmcnt(0)
	v_mfma_f32_32x32x16_bf16 v[48:63], v[2:5], v[80:83], v[48:63]
	ds_read_b128 v[80:83], v0 offset:128
	ds_read_b128 v[6:9], v108 offset:35216
	s_waitcnt lgkmcnt(1)
	v_mfma_f32_32x32x16_bf16 v[16:31], v[10:13], v[80:83], v[16:31]
	s_waitcnt lgkmcnt(0)
	v_mfma_f32_32x32x16_bf16 v[48:63], v[6:9], v[80:83], v[48:63]
	ds_read_b128 v[80:83], v0 offset:160
	ds_read_b128 v[10:13], v108 offset:35248
	s_waitcnt lgkmcnt(1)
	v_mfma_f32_32x32x16_bf16 v[16:31], v[2:5], v[80:83], v[16:31]
	s_waitcnt lgkmcnt(0)
	v_mfma_f32_32x32x16_bf16 v[48:63], v[10:13], v[80:83], v[48:63]
	ds_read_b128 v[80:83], v0 offset:192
	ds_read_b128 v[2:5], v108 offset:35280
	s_waitcnt lgkmcnt(1)
	v_mfma_f32_32x32x16_bf16 v[16:31], v[6:9], v[80:83], v[16:31]
	s_waitcnt lgkmcnt(0)
	v_mfma_f32_32x32x16_bf16 v[48:63], v[2:5], v[80:83], v[48:63]
	ds_read_b128 v[6:9], v0 offset:224
	ds_read_b128 v[2:5], v108 offset:35312
	s_waitcnt lgkmcnt(1)
	v_mfma_f32_32x32x16_bf16 v[16:31], v[10:13], v[6:9], v[16:31]
	s_waitcnt lgkmcnt(0)
	v_mfma_f32_32x32x16_bf16 v[48:63], v[2:5], v[6:9], v[48:63]
.LBB0_1516:
	s_or_b64 exec, exec, s[2:3]
	s_movk_i32 s0, 0x7c
	v_cmp_lt_u32_e32 vcc, s0, v109
	s_and_saveexec_b64 s[2:3], vcc
	s_cbranch_execz .LBB0_1518
	v_subrev_u32_e32 v0, 61, v105
	v_min_u32_e32 v0, 0x80, v0
	s_movk_i32 s0, 0x110
	v_mad_u32_u24 v0, v0, s0, v106
	ds_read_b128 v[2:5], v108 offset:34832
	ds_read_b128 v[6:9], v0
	ds_read_b128 v[10:13], v108 offset:34768
	s_waitcnt lgkmcnt(1)
	v_mfma_f32_32x32x16_bf16 v[48:63], v[2:5], v[6:9], v[48:63]
	s_waitcnt lgkmcnt(0)
	v_mfma_f32_32x32x16_bf16 v[16:31], v[10:13], v[6:9], v[16:31]
	ds_read_b128 v[6:9], v108 offset:34864
	ds_read_b128 v[10:13], v0 offset:32
	ds_read_b128 v[80:83], v108 offset:34800
	s_waitcnt lgkmcnt(1)
	v_mfma_f32_32x32x16_bf16 v[48:63], v[6:9], v[10:13], v[48:63]
	s_waitcnt lgkmcnt(0)
	v_mfma_f32_32x32x16_bf16 v[16:31], v[80:83], v[10:13], v[16:31]
	ds_read_b128 v[80:83], v0 offset:64
	ds_read_b128 v[10:13], v108 offset:34896
	s_waitcnt lgkmcnt(1)
	v_mfma_f32_32x32x16_bf16 v[16:31], v[2:5], v[80:83], v[16:31]
	s_waitcnt lgkmcnt(0)
	v_mfma_f32_32x32x16_bf16 v[48:63], v[10:13], v[80:83], v[48:63]
	ds_read_b128 v[80:83], v0 offset:96
	ds_read_b128 v[2:5], v108 offset:34928
	s_waitcnt lgkmcnt(1)
	v_mfma_f32_32x32x16_bf16 v[16:31], v[6:9], v[80:83], v[16:31]
	s_waitcnt lgkmcnt(0)
	v_mfma_f32_32x32x16_bf16 v[48:63], v[2:5], v[80:83], v[48:63]
	ds_read_b128 v[80:83], v0 offset:128
	ds_read_b128 v[6:9], v108 offset:34960
	s_waitcnt lgkmcnt(1)
	v_mfma_f32_32x32x16_bf16 v[16:31], v[10:13], v[80:83], v[16:31]
	s_waitcnt lgkmcnt(0)
	v_mfma_f32_32x32x16_bf16 v[48:63], v[6:9], v[80:83], v[48:63]
	ds_read_b128 v[80:83], v0 offset:160
	ds_read_b128 v[10:13], v108 offset:34992
	s_waitcnt lgkmcnt(1)
	v_mfma_f32_32x32x16_bf16 v[16:31], v[2:5], v[80:83], v[16:31]
	s_waitcnt lgkmcnt(0)
	v_mfma_f32_32x32x16_bf16 v[48:63], v[10:13], v[80:83], v[48:63]
	ds_read_b128 v[80:83], v0 offset:192
	ds_read_b128 v[2:5], v108 offset:35024
	s_waitcnt lgkmcnt(1)
	v_mfma_f32_32x32x16_bf16 v[16:31], v[6:9], v[80:83], v[16:31]
	s_waitcnt lgkmcnt(0)
	v_mfma_f32_32x32x16_bf16 v[48:63], v[2:5], v[80:83], v[48:63]
	ds_read_b128 v[6:9], v0 offset:224
	ds_read_b128 v[2:5], v108 offset:35056
	s_waitcnt lgkmcnt(1)
	v_mfma_f32_32x32x16_bf16 v[16:31], v[10:13], v[6:9], v[16:31]
	s_waitcnt lgkmcnt(0)
	v_mfma_f32_32x32x16_bf16 v[48:63], v[2:5], v[6:9], v[48:63]
; #define MFMA(a, b, c) __builtin_amdgcn_mfma_f32_32x32x16_bf16((a), (b), (c), 0, 0, 0)
; __device__ __forceinline__ void toeplitz_item(const Params& p, int layer, int half, int c, bf16* sm, int dry, unsigned* done_ctr) {
;     ...
;       } else {
; #pragma unroll
;         for (int ks = 0; ks < 8; ++ks) {
;           const s8v a0 = *(const s8v*)(ap0 + 16 * ks), a1 = *(const s8v*)(ap0 - 32 + 16 * ks);
;           const s8v b1 = *(const s8v*)(bp1 + 16 * ks);
;           acc[0][1] = MFMA(a0, b1, acc[0][1]);
;           acc[1][1] = MFMA(a1, b1, acc[1][1]);
;         }
;       }
.LBB0_1518:
	s_or_b64 exec, exec, s[2:3]
	s_movk_i32 s0, 0x7d
	v_cmp_lt_u32_e32 vcc, s0, v109
	s_and_saveexec_b64 s[2:3], vcc
	s_cbranch_execz .LBB0_1520
	v_subrev_u32_e32 v0, 62, v105
	v_min_u32_e32 v0, 0x80, v0
	s_movk_i32 s0, 0x110
	v_mad_u32_u24 v0, v0, s0, v106
	ds_read_b128 v[2:5], v108 offset:34576
	ds_read_b128 v[6:9], v0
	ds_read_b128 v[10:13], v108 offset:34512
	s_waitcnt lgkmcnt(1)
	v_mfma_f32_32x32x16_bf16 v[48:63], v[2:5], v[6:9], v[48:63]
	s_waitcnt lgkmcnt(0)
	v_mfma_f32_32x32x16_bf16 v[16:31], v[10:13], v[6:9], v[16:31]
	ds_read_b128 v[6:9], v108 offset:34608
	ds_read_b128 v[10:13], v0 offset:32
	ds_read_b128 v[80:83], v108 offset:34544
	s_waitcnt lgkmcnt(1)
	v_mfma_f32_32x32x16_bf16 v[48:63], v[6:9], v[10:13], v[48:63]
	s_waitcnt lgkmcnt(0)
	v_mfma_f32_32x32x16_bf16 v[16:31], v[80:83], v[10:13], v[16:31]
	ds_read_b128 v[80:83], v0 offset:64
	ds_read_b128 v[10:13], v108 offset:34640
	s_waitcnt lgkmcnt(1)
	v_mfma_f32_32x32x16_bf16 v[16:31], v[2:5], v[80:83], v[16:31]
	s_waitcnt lgkmcnt(0)
	v_mfma_f32_32x32x16_bf16 v[48:63], v[10:13], v[80:83], v[48:63]
	ds_read_b128 v[80:83], v0 offset:96
	ds_read_b128 v[2:5], v108 offset:34672
	s_waitcnt lgkmcnt(1)
	v_mfma_f32_32x32x16_bf16 v[16:31], v[6:9], v[80:83], v[16:31]
	s_waitcnt lgkmcnt(0)
	v_mfma_f32_32x32x16_bf16 v[48:63], v[2:5], v[80:83], v[48:63]
	ds_read_b128 v[80:83], v0 offset:128
	ds_read_b128 v[6:9], v108 offset:34704
	s_waitcnt lgkmcnt(1)
	v_mfma_f32_32x32x16_bf16 v[16:31], v[10:13], v[80:83], v[16:31]
	s_waitcnt lgkmcnt(0)
	v_mfma_f32_32x32x16_bf16 v[48:63], v[6:9], v[80:83], v[48:63]
	ds_read_b128 v[80:83], v0 offset:160
	ds_read_b128 v[10:13], v108 offset:34736
	s_waitcnt lgkmcnt(1)
	v_mfma_f32_32x32x16_bf16 v[16:31], v[2:5], v[80:83], v[16:31]
	s_waitcnt lgkmcnt(0)
	v_mfma_f32_32x32x16_bf16 v[48:63], v[10:13], v[80:83], v[48:63]
	ds_read_b128 v[80:83], v0 offset:192
	ds_read_b128 v[2:5], v108 offset:34768
	s_waitcnt lgkmcnt(1)
	v_mfma_f32_32x32x16_bf16 v[16:31], v[6:9], v[80:83], v[16:31]
	s_waitcnt lgkmcnt(0)
	v_mfma_f32_32x32x16_bf16 v[48:63], v[2:5], v[80:83], v[48:63]
	ds_read_b128 v[6:9], v0 offset:224
	ds_read_b128 v[2:5], v108 offset:34800
	s_waitcnt lgkmcnt(1)
	v_mfma_f32_32x32x16_bf16 v[16:31], v[10:13], v[6:9], v[16:31]
	s_waitcnt lgkmcnt(0)
	v_mfma_f32_32x32x16_bf16 v[48:63], v[2:5], v[6:9], v[48:63]
.LBB0_1520:
	s_or_b64 exec, exec, s[2:3]
	v_cmp_ne_u32_e32 vcc, 0, v107
	s_and_saveexec_b64 s[2:3], vcc
	s_cbranch_execz .LBB0_1522
	v_subrev_u32_e32 v0, 63, v105
	v_min_u32_e32 v0, 0x80, v0
	s_movk_i32 s0, 0x110
	v_mad_u32_u24 v0, v0, s0, v106
	ds_read_b128 v[2:5], v108 offset:34320
	ds_read_b128 v[6:9], v0
	ds_read_b128 v[10:13], v108 offset:34256
	s_waitcnt lgkmcnt(1)
	v_mfma_f32_32x32x16_bf16 v[48:63], v[2:5], v[6:9], v[48:63]
	s_waitcnt lgkmcnt(0)
	v_mfma_f32_32x32x16_bf16 v[16:31], v[10:13], v[6:9], v[16:31]
	ds_read_b128 v[6:9], v108 offset:34352
	ds_read_b128 v[10:13], v0 offset:32
	ds_read_b128 v[80:83], v108 offset:34288
	s_waitcnt lgkmcnt(1)
	v_mfma_f32_32x32x16_bf16 v[48:63], v[6:9], v[10:13], v[48:63]
	s_waitcnt lgkmcnt(0)
	v_mfma_f32_32x32x16_bf16 v[16:31], v[80:83], v[10:13], v[16:31]
	ds_read_b128 v[80:83], v0 offset:64
	ds_read_b128 v[10:13], v108 offset:34384
	s_waitcnt lgkmcnt(1)
	v_mfma_f32_32x32x16_bf16 v[16:31], v[2:5], v[80:83], v[16:31]
	s_waitcnt lgkmcnt(0)
	v_mfma_f32_32x32x16_bf16 v[48:63], v[10:13], v[80:83], v[48:63]
	ds_read_b128 v[80:83], v0 offset:96
	ds_read_b128 v[2:5], v108 offset:34416
	s_waitcnt lgkmcnt(1)
	v_mfma_f32_32x32x16_bf16 v[16:31], v[6:9], v[80:83], v[16:31]
	s_waitcnt lgkmcnt(0)
	v_mfma_f32_32x32x16_bf16 v[48:63], v[2:5], v[80:83], v[48:63]
	ds_read_b128 v[80:83], v0 offset:128
	ds_read_b128 v[6:9], v108 offset:34448
	s_waitcnt lgkmcnt(1)
	v_mfma_f32_32x32x16_bf16 v[16:31], v[10:13], v[80:83], v[16:31]
	s_waitcnt lgkmcnt(0)
	v_mfma_f32_32x32x16_bf16 v[48:63], v[6:9], v[80:83], v[48:63]
	ds_read_b128 v[80:83], v0 offset:160
	ds_read_b128 v[10:13], v108 offset:34480
	s_waitcnt lgkmcnt(1)
	v_mfma_f32_32x32x16_bf16 v[16:31], v[2:5], v[80:83], v[16:31]
	s_waitcnt lgkmcnt(0)
	v_mfma_f32_32x32x16_bf16 v[48:63], v[10:13], v[80:83], v[48:63]
	ds_read_b128 v[80:83], v0 offset:192
	ds_read_b128 v[2:5], v108 offset:34512
	s_waitcnt lgkmcnt(1)
	v_mfma_f32_32x32x16_bf16 v[16:31], v[6:9], v[80:83], v[16:31]
	s_waitcnt lgkmcnt(0)
	v_mfma_f32_32x32x16_bf16 v[48:63], v[2:5], v[80:83], v[48:63]
	ds_read_b128 v[6:9], v0 offset:224
	ds_read_b128 v[2:5], v108 offset:34544
	s_waitcnt lgkmcnt(1)
	v_mfma_f32_32x32x16_bf16 v[16:31], v[10:13], v[6:9], v[16:31]
	s_waitcnt lgkmcnt(0)
	v_mfma_f32_32x32x16_bf16 v[48:63], v[2:5], v[6:9], v[48:63]
